# mix2 loop top: first K/V image write waits until the previous chunk's output stores have all drained (vmcnt 7 -> 4)
# speedup vs baseline: 1.0066x; 1.0066x over previous
; #define LAS __attribute__((address_space(3)))
; __device__ void mix_sweep(const Params& P, LAS unsigned char* lds, int tok0, int pos0, int seqlen, int hd, int dir, bool state_only, bool final_pass,
;                           f32x4 (&Cacc)[9], float& m_state, float& aseg_sum, float lgam) {
;     ...
;         const int c = dir ? 7 - ci : ci; const int tok = tok0 + c * 128;
;         __syncthreads();
;         int tl = tid; asm volatile("" : "+v"(tl));
;         if (!state_only) {
; #pragma unroll
;             for (int it = 0; it < 4; ++it) { const int item = tl + 512 * it, r = item >> 4, ch = item & 15; t[0][it] = *(const u32x4*)(proj + (size_t)(tok + r) * NPROJ + qcol + 8 * ch); } }
; #pragma unroll
;     ...
; #pragma unroll
;             for (int it = 0; it < 4; ++it) { const int item = tl + 512 * it, r = item >> 4, ch = item & 15; *(LAS u32x4*)(img + offb(r, ch)) = t[which][it]; } }
;         if (ci < 7) { const int cn = dir ? 6 - ci : ci + 1; const int tokn = tok0 + cn * 128;
; #pragma unroll
;             for (int which = 1; which < 3; ++which) { const int cb = which == 1 ? kcol : vcolg;
; #pragma unroll
;                 for (int it = 0; it < 4; ++it) { const int item = tl + 512 * it, r = item >> 4, ch = item & 15; t[which][it] = *(const u32x4*)(proj + (size_t)(tokn + r) * NPROJ + cb + 8 * ch); } } }
.LBB0_98:
	s_xor_b32 s15, s7, 0x380
	s_and_b64 s[16:17], s[8:9], exec
	s_cselect_b32 s89, s7, s15
	v_mov_b32_e32 v92, v161
	s_add_i32 s89, s89, s79
	s_waitcnt lgkmcnt(0)
	s_barrier
	s_cmpk_eq_i32 s87, 0xfa00
	v_lshlrev_b32_e32 v0, 3, v92
	v_ashrrev_i32_e32 v72, 4, v92
	v_and_b32_e32 v0, 0x78, v0
	v_add_u32_e32 v74, s89, v72
	v_lshlrev_b32_e32 v0, 1, v0
	v_ashrrev_i32_e32 v75, 31, v74
	v_lshl_add_u64 v[88:89], s[36:37], 0, v[0:1]
	v_lshlrev_b64 v[74:75], 13, v[74:75]
	v_add_u32_e32 v73, 0x200, v92
	v_lshl_add_u64 v[74:75], v[88:89], 0, v[74:75]
	v_ashrrev_i32_e32 v73, 4, v73
	global_load_dwordx4 v[76:79], v[74:75], off
	v_add_u32_e32 v74, s89, v73
	v_ashrrev_i32_e32 v75, 31, v74
	v_lshlrev_b64 v[74:75], 13, v[74:75]
	v_lshl_add_u64 v[74:75], v[88:89], 0, v[74:75]
	global_load_dwordx4 v[80:83], v[74:75], off
	v_add_u32_e32 v74, 0x400, v92
	v_ashrrev_i32_e32 v74, 4, v74
	v_add_u32_e32 v75, 0x600, v92
	v_add_u32_e32 v84, s89, v74
	v_ashrrev_i32_e32 v75, 4, v75
	v_ashrrev_i32_e32 v85, 31, v84
	v_add_u32_e32 v90, s89, v75
	v_lshlrev_b64 v[84:85], 13, v[84:85]
	v_ashrrev_i32_e32 v91, 31, v90
	v_lshl_add_u64 v[84:85], v[88:89], 0, v[84:85]
	v_lshlrev_b64 v[90:91], 13, v[90:91]
	global_load_dwordx4 v[84:87], v[84:85], off
	v_lshl_add_u64 v[88:89], v[88:89], 0, v[90:91]
	global_load_dwordx4 v[88:91], v[88:89], off
	v_lshlrev_b32_e32 v94, 2, v72
	v_and_b32_e32 v92, 15, v92
	v_and_b32_e32 v94, 12, v94
	v_bfe_u32 v95, v72, 2, 2
	v_bitop3_b32 v94, v94, v92, v95 bitop3:0x36
	v_lshlrev_b32_e32 v96, 2, v73
	v_lshlrev_b32_e32 v93, 8, v72
	v_lshlrev_b32_e32 v94, 4, v94
	v_and_b32_e32 v96, 12, v96
	v_bfe_u32 v97, v73, 2, 2
	v_add3_u32 v95, s85, v94, v93
	v_bitop3_b32 v96, v96, v92, v97 bitop3:0x36
	v_lshlrev_b32_e32 v98, 2, v74
	s_waitcnt vmcnt(4)
	ds_write_b128 v95, v[56:59]
	v_lshlrev_b32_e32 v95, 8, v73
	v_lshlrev_b32_e32 v96, 4, v96
	v_and_b32_e32 v98, 12, v98
	v_bfe_u32 v99, v74, 2, 2
	v_add3_u32 v97, s85, v96, v95
	v_bitop3_b32 v98, v98, v92, v99 bitop3:0x36
	v_lshlrev_b32_e32 v100, 2, v75
	s_waitcnt vmcnt(6)
	ds_write_b128 v97, v[60:63]
	v_lshlrev_b32_e32 v97, 8, v74
	v_lshlrev_b32_e32 v98, 4, v98
	v_and_b32_e32 v100, 12, v100
	v_bfe_u32 v101, v75, 2, 2
	v_add3_u32 v99, s85, v98, v97
	v_bitop3_b32 v92, v100, v92, v101 bitop3:0x36
	s_waitcnt vmcnt(5)
	ds_write_b128 v99, v[64:67]
	v_lshlrev_b32_e32 v99, 8, v75
	v_lshlrev_b32_e32 v92, 4, v92
	v_add3_u32 v100, s85, v92, v99
	v_add3_u32 v93, 0, v94, v93
	v_add3_u32 v94, 0, v96, v95
	v_add3_u32 v95, 0, v98, v97
	v_add3_u32 v92, 0, v92, v99
	s_waitcnt vmcnt(4)
	ds_write_b128 v100, v[68:71]
	ds_write_b128 v93, v[40:43] offset:32768
	ds_write_b128 v94, v[44:47] offset:32768
	ds_write_b128 v95, v[48:51] offset:32768
	ds_write_b128 v92, v[52:55] offset:32768
	s_waitcnt vmcnt(3)
	ds_write_b128 v93, v[76:79]
	s_waitcnt vmcnt(2)
	ds_write_b128 v94, v[80:83]
	s_waitcnt vmcnt(1)
	ds_write_b128 v95, v[84:87]
	s_waitcnt vmcnt(0)
	ds_write_b128 v92, v[88:91]
	s_cbranch_scc1 .LBB0_100
	s_and_b64 s[16:17], s[8:9], exec
	s_cselect_b32 s15, s83, s86
	s_lshl_b32 s15, s15, 7
	s_add_i32 s15, s15, s79
	v_add_u32_e32 v40, s15, v72
	v_add_u32_e32 v42, s15, v73
	v_add_u32_e32 v50, s15, v74
	v_add_u32_e32 v52, s15, v75
	v_lshl_add_u64 v[56:57], s[22:23], 0, v[0:1]
	v_ashrrev_i32_e32 v41, 31, v40
	v_ashrrev_i32_e32 v43, 31, v42
	v_ashrrev_i32_e32 v51, 31, v50
	v_ashrrev_i32_e32 v53, 31, v52
	s_mov_b32 s15, s39
	v_lshlrev_b64 v[58:59], 13, v[40:41]
	v_lshl_add_u64 v[48:49], v[56:57], 0, s[38:39]
	v_lshlrev_b64 v[60:61], 13, v[42:43]
	v_lshlrev_b64 v[64:65], 13, v[50:51]
	v_lshlrev_b64 v[66:67], 13, v[52:53]
	v_lshl_add_u64 v[68:69], v[56:57], 0, s[14:15]
	v_lshl_add_u64 v[40:41], v[48:49], 0, v[58:59]
	v_lshl_add_u64 v[44:45], v[48:49], 0, v[60:61]
	v_lshl_add_u64 v[50:51], v[48:49], 0, v[64:65]
	v_lshl_add_u64 v[52:53], v[48:49], 0, v[66:67]
	v_lshl_add_u64 v[56:57], v[68:69], 0, v[58:59]
	v_lshl_add_u64 v[60:61], v[68:69], 0, v[60:61]
	v_lshl_add_u64 v[64:65], v[68:69], 0, v[64:65]
	v_lshl_add_u64 v[68:69], v[68:69], 0, v[66:67]
	global_load_dwordx4 v[40:43], v[40:41], off
	s_nop 0
	global_load_dwordx4 v[44:47], v[44:45], off
	s_nop 0
	global_load_dwordx4 v[48:51], v[50:51], off
	s_nop 0
	global_load_dwordx4 v[52:55], v[52:53], off
	s_nop 0
	global_load_dwordx4 v[56:59], v[56:57], off
	s_nop 0
	global_load_dwordx4 v[60:63], v[60:61], off
	s_nop 0
	global_load_dwordx4 v[64:67], v[64:65], off
	s_nop 0
	global_load_dwordx4 v[68:71], v[68:69], off
